# XCD-local GEMM seams guarded by a runtime census check (falls back to the full barrier if blocks with equal id mod 8 do not share an XCD)
# speedup vs baseline: 1.0133x; 1.0018x over previous
_Z6mk_fwd4Args:
	s_mov_b32 s79, s2
	s_mov_b64 s[2:3], s[0:1]
	s_load_dwordx2 s[74:75], s[0:1], 0xa8
	s_load_dword s97, s[0:1], 0xb0
	s_load_dword s2, s[2:3], 0x98
	v_and_b32_e32 v210, 0x3ff, v0
	v_cmp_gt_u32_e32 vcc, 8, v210
	s_waitcnt lgkmcnt(0)
	v_writelane_b32 v254, s2, 0
	s_mov_b64 s[2:3], s[0:1]
	s_load_dword s84, s[2:3], 0x9c
	s_mov_b64 s[2:3], s[0:1]
	s_load_dword s6, s[2:3], 0xa0
	s_add_u32 s2, s0, 0xa8
	s_addc_u32 s3, s1, 0
	v_writelane_b32 v254, s2, 1
	s_nop 1
	v_writelane_b32 v254, s3, 2
	s_and_saveexec_b64 s[2:3], vcc
	v_lshl_add_u32 v1, v210, 2, 0
	v_add_u32_e32 v1, 0x23fc0, v1
	v_mov_b32_e32 v2, 0
	ds_write_b32 v1, v2
	s_or_b64 exec, exec, s[2:3]
	s_mov_b64 s[2:3], s[0:1]
	s_waitcnt lgkmcnt(0)
	s_barrier
	s_load_dwordx2 s[2:3], s[2:3], 0x90
	s_mov_b32 s7, 0
	v_cmp_eq_u32_e32 vcc, 0, v210
	s_waitcnt lgkmcnt(0)
	s_add_u32 s80, s2, 0x10000
	s_addc_u32 s81, s3, 0
	s_cmp_lg_u32 s6, 0
	s_cselect_b64 s[2:3], -1, 0
	v_writelane_b32 v254, s2, 3
	s_cmp_eq_u32 s6, 0
	s_nop 0
	v_writelane_b32 v254, s3, 4
	s_cbranch_scc1 .LBB0_7
	s_mov_b64 s[2:3], s[0:1]
	s_load_dwordx2 s[2:3], s[2:3], 0x90
	s_getreg_b32 s4, hwreg(HW_REG_XCC_ID, 0, 4)
	s_waitcnt lgkmcnt(0)
	s_add_u32 s80, s2, 0x10000
	s_addc_u32 s81, s3, 0
	s_and_b32 s55, s4, 15
	s_and_saveexec_b64 s[2:3], vcc
	s_cbranch_execz .LBB0_6
	s_mov_b64 s[4:5], exec
	v_mbcnt_lo_u32_b32 v1, s4, 0
	v_mbcnt_hi_u32_b32 v1, s5, v1
	v_cmp_eq_u32_e32 vcc, 0, v1
	s_and_b64 s[6:7], exec, vcc
	s_mov_b64 exec, s[6:7]
	s_cbranch_execz .LBB0_6
	s_lshl_b32 s6, s55, 8
	s_bcnt1_i32_b64 s4, s[4:5]
	v_mov_b32_e32 v1, s6
	v_mov_b32_e32 v2, s4
	global_atomic_add v1, v2, s[80:81] offset:1024
	s_and_b32 s4, s79, 7
	s_lshl_b32 s4, 1, s4
	v_mov_b32_e32 v3, s4
	v_add_u32_e32 v4, 0x4000, v1
	global_atomic_or v4, v3, s[80:81]

.LBB0_253:
	s_getreg_b32 s0, hwreg(HW_REG_XCC_ID, 0, 4)
	s_and_b32 s0, s0, 15
	s_lshl_b32 s0, s0, 8
	s_add_i32 s0, s0, 0x4000
	v_mov_b32_e32 v2, s0
	global_load_dword v4, v2, s[80:81] sc1
	s_waitcnt vmcnt(0)
	v_readfirstlane_b32 s0, v4
	s_nop 3
	s_bcnt1_i32_b32 s0, s0
	s_cmp_eq_u32 s0, 1
	s_cbranch_scc1 .Lxcd_chk_ok
	v_mov_b32_e32 v2, 0x5000
	v_mov_b32_e32 v4, 1
	global_atomic_or v2, v4, s[80:81]
	s_waitcnt vmcnt(0)

.LBB0_497:
	v_mov_b32_e32 v4, 0x5000
	global_load_dword v5, v4, s[80:81] sc1
	v_mov_b32_e32 v4, 0x23fd4
	s_waitcnt vmcnt(0)
	ds_write_b32 v4, v5
	s_waitcnt lgkmcnt(0)
	s_xor_b64 s[2:3], s[2:3], -1
	v_writelane_b32 v255, s2, 23
	s_nop 1
	v_writelane_b32 v255, s3, 24
	v_readlane_b32 s2, v254, 0
	s_cmp_le_i32 s2, s1
	s_cselect_b64 s[2:3], -1, 0
	s_cmp_lt_i32 s1, s84
	s_cselect_b64 s[4:5], -1, 0
	s_and_b64 s[2:3], s[2:3], s[4:5]
	s_andn2_b64 vcc, exec, s[2:3]
	s_cbranch_vccnz .LBB0_719
	v_readlane_b32 s2, v254, 5
	v_readlane_b32 s3, v254, 6
	s_mov_b32 s1, s79
	s_load_dwordx2 s[46:47], s[2:3], 0x90
	s_waitcnt lgkmcnt(0)
	s_add_u32 s28, s46, 0x15100000
	s_addc_u32 s29, s47, 0
	s_cmp_lt_i32 s1, 64
	s_cbranch_scc0 .LBB0_513
	v_readlane_b32 s2, v255, 21
	s_lshl_b32 s7, s2, 1
	s_add_u32 s8, s46, 0x13000000
	s_addc_u32 s9, s47, 0
	s_add_u32 s2, s46, 0x180000
	s_addc_u32 s3, s47, 0
	s_bitcmp1_b32 s1, 0
	s_cselect_b64 s[18:19], -1, 0
	s_mov_b32 s13, s1
	s_branch .LBB0_501

.LBB0_1174:
	s_andn2_saveexec_b64 s[4:5], s[4:5]
	s_cbranch_execz .LBB0_1190
	v_mov_b32_e32 v0, 0x23fd4
	ds_read_b32 v0, v0
	s_waitcnt lgkmcnt(0)
	v_readfirstlane_b32 s4, v0
	s_nop 3
	s_cmp_eq_u32 s4, 0
	s_cbranch_scc1 .Lxcd_local_b
	v_readlane_b32 s4, v254, 61
	buffer_wbl2 sc1
	s_waitcnt lgkmcnt(0)
	s_waitcnt vmcnt(0)
	v_readlane_b32 s5, v254, 62
	v_mov_b32_e32 v0, 1
	v_sub_u32_e32 v4, 0, v2
	s_mov_b64 s[18:19], -1
	s_nop 1
	global_atomic_add v3, v1, v0, s[4:5] sc0
	v_cvt_f32_u32_e32 v0, v2
	v_readlane_b32 s4, v254, 63
	v_readlane_b32 s5, v255, 0
	v_rcp_iflag_f32_e32 v0, v0
	s_nop 0
	v_mul_f32_e32 v0, 0x4f7ffffe, v0
	v_cvt_u32_f32_e32 v0, v0
	v_mul_lo_u32 v4, v4, v0
	v_mul_hi_u32 v4, v0, v4
	v_add_u32_e32 v0, v0, v4
	s_waitcnt vmcnt(0)
	v_mul_hi_u32 v0, v3, v0
	v_mul_lo_u32 v4, v0, v2
	v_sub_u32_e32 v4, v3, v4
	v_cmp_ge_u32_e32 vcc, v4, v2
	v_add_u32_e32 v5, 1, v0
	v_add_u32_e32 v3, 1, v3
	v_cndmask_b32_e32 v0, v0, v5, vcc
	v_sub_u32_e32 v5, v4, v2
	v_cndmask_b32_e32 v4, v4, v5, vcc
	v_cmp_ge_u32_e32 vcc, v4, v2
	v_add_u32_e32 v4, 1, v0
	s_nop 0
	v_cndmask_b32_e32 v0, v0, v4, vcc
	v_mul_lo_u32 v4, v2, v0
	v_add_u32_e32 v2, v4, v2
	v_cmp_ne_u32_e32 vcc, v3, v2
	v_mov_b64_e32 v[2:3], s[4:5]
	s_and_saveexec_b64 s[4:5], vcc
	s_cbranch_execz .LBB0_1187
	v_readlane_b32 s8, v254, 63
	v_readlane_b32 s9, v255, 0
	s_mov_b64 s[28:29], 0
	s_nop 3
	global_load_dword v2, v1, s[8:9] sc1
	s_waitcnt vmcnt(0)
	v_cmp_eq_u32_e32 vcc, v2, v0
	s_and_saveexec_b64 s[18:19], vcc
	s_cbranch_execz .LBB0_1186
	s_mov_b32 s7, 1
	s_mov_b64 s[30:31], 0
	s_branch .LBB0_1179

.LBB0_1279:
	s_andn2_saveexec_b64 s[4:5], s[4:5]
	s_cbranch_execz .LBB0_1295
	v_mov_b32_e32 v0, 0x23fd4
	ds_read_b32 v0, v0
	s_waitcnt lgkmcnt(0)
	v_readfirstlane_b32 s4, v0
	s_nop 3
	s_cmp_eq_u32 s4, 0
	s_cbranch_scc1 .Lxcd_local_a
	v_readlane_b32 s4, v254, 61
	buffer_wbl2 sc1
	s_waitcnt lgkmcnt(0)
	s_waitcnt vmcnt(0)
	v_readlane_b32 s5, v254, 62
	v_mov_b32_e32 v0, 1
	v_sub_u32_e32 v4, 0, v2
	s_mov_b64 s[18:19], -1
	s_nop 1
	global_atomic_add v3, v1, v0, s[4:5] sc0
	v_cvt_f32_u32_e32 v0, v2
	v_readlane_b32 s4, v254, 63
	v_readlane_b32 s5, v255, 0
	v_rcp_iflag_f32_e32 v0, v0
	s_nop 0
	v_mul_f32_e32 v0, 0x4f7ffffe, v0
	v_cvt_u32_f32_e32 v0, v0
	v_mul_lo_u32 v4, v4, v0
	v_mul_hi_u32 v4, v0, v4
	v_add_u32_e32 v0, v0, v4
	s_waitcnt vmcnt(0)
	v_mul_hi_u32 v0, v3, v0
	v_mul_lo_u32 v4, v0, v2
	v_sub_u32_e32 v4, v3, v4
	v_cmp_ge_u32_e32 vcc, v4, v2
	v_add_u32_e32 v5, 1, v0
	v_add_u32_e32 v3, 1, v3
	v_cndmask_b32_e32 v0, v0, v5, vcc
	v_sub_u32_e32 v5, v4, v2
	v_cndmask_b32_e32 v4, v4, v5, vcc
	v_cmp_ge_u32_e32 vcc, v4, v2
	v_add_u32_e32 v4, 1, v0
	s_nop 0
	v_cndmask_b32_e32 v0, v0, v4, vcc
	v_mul_lo_u32 v4, v2, v0
	v_add_u32_e32 v2, v4, v2
	v_cmp_ne_u32_e32 vcc, v3, v2
	v_mov_b64_e32 v[2:3], s[4:5]
	s_and_saveexec_b64 s[4:5], vcc
	s_cbranch_execz .LBB0_1292
	v_readlane_b32 s8, v254, 63
	v_readlane_b32 s9, v255, 0
	s_mov_b64 s[28:29], 0
	s_nop 3
	global_load_dword v2, v1, s[8:9] sc1
	s_waitcnt vmcnt(0)
	v_cmp_eq_u32_e32 vcc, v2, v0
	s_and_saveexec_b64 s[18:19], vcc
	s_cbranch_execz .LBB0_1291
	s_mov_b32 s1, 1
	s_mov_b64 s[30:31], 0
	s_branch .LBB0_1284
